# MLA attention loop too: KN/KPE/V^T tiles go HBM->LDS directly (global_load_lds_dwordx4) into unpadded XOR-swizzled images; V step-B addresses via inst offset + M0 bias
# speedup vs baseline: 1.1029x; 1.0391x over previous
;   DI void init_offs() {
; #pragma unroll
;     for (int q = 0; q < NKL; ++q) {
;       const int c = tid + 256 * q, row = c / KCH, cc = c % KCH;
;       koff[q] = (DQK == 96 && cc >= 8) ? row * 32 + (cc - 8) * 8 : row * kpitch + cc * 8;
;     }
; #pragma unroll
;     for (int q = 0; q < 2; ++q) { const int c = tid + 256 * q, dv = c >> 3, kc = c & 7; voff[q] = dv * MPAD + kc * 8; }
;   }
;   DI void gload_k(int t) {
;     const int row0 = rowk0 + t * 64;
;     const u16* kt = Kb + (size_t)row0 * kpitch;
;     const u16* pt = KPEb + (size_t)row0 * 32;
; #pragma unroll
;     for (int q = 0; q < NKL; ++q) {
;       const int c = tid + 256 * q, cc = c % KCH;
;       rk[q] = ldg16(((DQK == 96 && cc >= 8) ? pt : kt) + koff[q]);
;     }
;   }
;   DI void gload_v(int t) {
;     const u16* vt = Vt + (rowk0 + t * 64);
; #pragma unroll
;     for (int q = 0; q < 2; ++q) rv[q] = ldg16(vt + voff[q]);
;   }
;   DI void sstore_k(int buf) {
; #pragma unroll
;     for (int q = 0; q < NKL; ++q) {
;       const int c = tid + 256 * q, row = c / KCH, cc = c % KCH;
;       *(u32x4*)(sK + buf * KBUF + row * KP + cc * 8) = rk[q];
;     }
;   }
;   DI void sstore_v(int buf) {
; #pragma unroll
;     for (int q = 0; q < 2; ++q) {
;       const int c = tid + 256 * q, dv = c >> 3, kc = c & 7;
;       *(u32x4*)(sV + buf * VBUF + dv * GP + kc * 8) = rv[q];
;     }
;   }
; template <int DQK>
; DI void attn_item(const u16* __restrict__ Qb, int qpitch, const u16* __restrict__ Kb, int kpitch, const u16* __restrict__ KPEb,
;                   const u16* __restrict__ Vt, float* __restrict__ ssq, int rowq0, int rowk0, int nt, char* smem, int tid, bool dry) {
;     ...
;   c.gload_k(0); c.gload_v(0);
;   __syncthreads();
;   c.sstore_k(0); c.sstore_v(0);
;   if (nt > 1) c.gload_k(1);
;   __syncthreads();
;   c.qk(0, sa);
.Lm_entry:
	v_mov_b32_e32 v181, 0
	v_mov_b32_e32 v182, 0
	v_mov_b32_e32 v183, 0
	v_mov_b32_e32 v238, 0
	v_mov_b32_e32 v239, 0
	s_waitcnt vmcnt(0)
	v_mov_b32_e32 v100, v245
	v_mul_u32_u24_e32 v101, 0xaaab, v100
	v_lshrrev_b32_e32 v101, 19, v101
	v_mul_u32_u24_e32 v102, 12, v101
	v_sub_u32_e32 v102, v100, v102
	v_bfe_u32 v103, v101, 1, 3
	v_xor_b32_e32 v103, v103, v102
	v_and_b32_e32 v103, 7, v103
	v_lshlrev_b32_e32 v103, 4, v103
	v_lshl_add_u32 v103, v101, 7, v103
	v_add_u32_e32 v103, 13312, v103
	v_bfe_u32 v104, v101, 2, 2
	v_xor_b32_e32 v104, v104, v102
	v_and_b32_e32 v104, 3, v104
	v_lshlrev_b32_e32 v104, 4, v104
	v_lshl_add_u32 v104, v101, 6, v104
	v_add_u32_e32 v104, 21504, v104
	v_cmp_gt_u32_e32 vcc, 8, v102
	s_nop 1
	v_cndmask_b32_e32 v103, v104, v103, vcc
	ds_write_b128 v103, v[160:163]
	v_add_u32_e32 v100, 256, v245
	v_mul_u32_u24_e32 v101, 0xaaab, v100
	v_lshrrev_b32_e32 v101, 19, v101
	v_mul_u32_u24_e32 v102, 12, v101
	v_sub_u32_e32 v102, v100, v102
	v_bfe_u32 v103, v101, 1, 3
	v_xor_b32_e32 v103, v103, v102
	v_and_b32_e32 v103, 7, v103
	v_lshlrev_b32_e32 v103, 4, v103
	v_lshl_add_u32 v103, v101, 7, v103
	v_add_u32_e32 v103, 13312, v103
	v_bfe_u32 v104, v101, 2, 2
	v_xor_b32_e32 v104, v104, v102
	v_and_b32_e32 v104, 3, v104
	v_lshlrev_b32_e32 v104, 4, v104
	v_lshl_add_u32 v104, v101, 6, v104
	v_add_u32_e32 v104, 21504, v104
	v_cmp_gt_u32_e32 vcc, 8, v102
	s_nop 1
	v_cndmask_b32_e32 v103, v104, v103, vcc
	ds_write_b128 v103, v[164:167]
	v_add_u32_e32 v100, 512, v245
	v_mul_u32_u24_e32 v101, 0xaaab, v100
	v_lshrrev_b32_e32 v101, 19, v101
	v_mul_u32_u24_e32 v102, 12, v101
	v_sub_u32_e32 v102, v100, v102
	v_bfe_u32 v103, v101, 1, 3
	v_xor_b32_e32 v103, v103, v102
	v_and_b32_e32 v103, 7, v103
	v_lshlrev_b32_e32 v103, 4, v103
	v_lshl_add_u32 v103, v101, 7, v103
	v_add_u32_e32 v103, 13312, v103
	v_bfe_u32 v104, v101, 2, 2
	v_xor_b32_e32 v104, v104, v102
	v_and_b32_e32 v104, 3, v104
	v_lshlrev_b32_e32 v104, 4, v104
	v_lshl_add_u32 v104, v101, 6, v104
	v_add_u32_e32 v104, 21504, v104
	v_cmp_gt_u32_e32 vcc, 8, v102
	s_nop 1
	v_cndmask_b32_e32 v103, v104, v103, vcc
	ds_write_b128 v103, v[168:171]
	v_lshrrev_b32_e32 v100, 3, v245
	v_and_b32_e32 v101, 7, v245
	v_bfe_u32 v102, v245, 4, 3
	v_xor_b32_e32 v101, v101, v102
	v_lshlrev_b32_e32 v101, 4, v101
	v_lshl_add_u32 v100, v100, 7, v101
	ds_write_b128 v100, v[172:175] offset:25600
	ds_write_b128 v100, v[176:179] offset:29696
	v_readfirstlane_b32 s45, v245
	s_nop 3
	s_lshr_b32 s45, s45, 6
	s_lshl_b32 s1, s45, 4
	v_lshrrev_b32_e32 v101, 3, v227
	v_lshrrev_b32_e32 v102, 4, v227
	v_and_b32_e32 v103, 7, v227
	v_xor_b32_e32 v103, v103, v102
	v_lshlrev_b32_e32 v103, 4, v103
	v_xor_b32_e32 v102, 64, v103
	v_add_u32_e32 v101, s1, v101
	v_lshl_add_u32 v104, v101, 10, v103
	v_lshl_add_u32 v106, v101, 10, v102
	v_add_u32_e32 v106, 0x1c00, v106
	v_mov_b32_e32 v105, 0
	v_mov_b32_e32 v107, 0
	v_mul_u32_u24_e32 v108, 0x20600, v101
	v_add_u32_e32 v110, v108, v102
	v_add_u32_e32 v108, v108, v103
	v_add_u32_e32 v110, 0x102c00, v110
	v_mov_b32_e32 v109, 0
	v_mov_b32_e32 v111, 0
	v_lshrrev_b32_e32 v112, 2, v227
	v_add_u32_e32 v112, s1, v112
	v_and_b32_e32 v113, 3, v227
	v_bfe_u32 v114, v227, 4, 2
	v_xor_b32_e32 v113, v113, v114
	v_lshlrev_b32_e32 v113, 4, v113
	v_lshl_add_u32 v112, v112, 6, v113
	v_mov_b32_e32 v113, 0
	s_sub_i32 s0, s44, 64
	s_ashr_i32 s1, s0, 31
	s_lshl_b64 s[20:21], s[0:1], 10
	s_lshl_b64 s[0:1], s[0:1], 6
	s_add_u32 s20, s26, s20
	s_addc_u32 s21, s27, s21
	s_add_u32 s0, s81, s0
	s_addc_u32 s1, s64, s1
	v_lshl_add_u64 v[170:171], v[104:105], 0, s[20:21]
	v_lshl_add_u64 v[172:173], v[106:107], 0, s[20:21]
	v_lshl_add_u64 v[174:175], v[112:113], 0, s[0:1]
	s_add_i32 s0, s44, 0xffffff80
	s_ashr_i32 s1, s0, 31
	s_lshl_b64 s[0:1], s[0:1], 1
	s_add_u32 s0, s35, s0
	s_addc_u32 s1, s30, s1
	v_lshl_add_u64 v[176:177], v[108:109], 0, s[0:1]
	v_lshl_add_u64 v[178:179], v[110:111], 0, s[0:1]
	s_mov_b32 s20, 0x10000
	s_mov_b32 s21, 0
	s_lshl_b32 s44, s45, 11
	s_lshl_b32 s45, s45, 10
	v_and_b32_e32 v100, 31, v227
	v_lshrrev_b32_e32 v101, 5, v227
	v_and_b32_e32 v102, 0x13, v100
	v_and_b32_e32 v103, 4, v100
	v_lshl_or_b32 v102, v103, 1, v102
	v_and_b32_e32 v103, 8, v100
	v_lshrrev_b32_e32 v103, 1, v103
	v_or_b32_e32 v102, v102, v103
	v_bfe_u32 v103, v102, 1, 3
	v_bfe_u32 v104, v100, 1, 3
	v_bfe_u32 v107, v102, 2, 2
	v_or_b32_e32 v105, 0, v101
	v_xor_b32_e32 v106, v105, v103
	v_lshlrev_b32_e32 v106, 4, v106
	v_lshl_add_u32 v160, v102, 7, v106
	v_xor_b32_e32 v106, v105, v104
	v_lshlrev_b32_e32 v106, 4, v106
	v_lshl_add_u32 v166, v100, 7, v106
	v_or_b32_e32 v105, 2, v101
	v_xor_b32_e32 v106, v105, v103
	v_lshlrev_b32_e32 v106, 4, v106
	v_lshl_add_u32 v161, v102, 7, v106
	v_xor_b32_e32 v106, v105, v104
	v_lshlrev_b32_e32 v106, 4, v106
	v_lshl_add_u32 v167, v100, 7, v106
	v_or_b32_e32 v105, 4, v101
	v_xor_b32_e32 v106, v105, v103
	v_lshlrev_b32_e32 v106, 4, v106
	v_lshl_add_u32 v162, v102, 7, v106
	v_xor_b32_e32 v106, v105, v104
	v_lshlrev_b32_e32 v106, 4, v106
	v_lshl_add_u32 v168, v100, 7, v106
	v_or_b32_e32 v105, 6, v101
	v_xor_b32_e32 v106, v105, v103
	v_lshlrev_b32_e32 v106, 4, v106
	v_lshl_add_u32 v163, v102, 7, v106
	v_xor_b32_e32 v106, v105, v104
	v_lshlrev_b32_e32 v106, 4, v106
	v_lshl_add_u32 v169, v100, 7, v106
	v_or_b32_e32 v105, 0, v101
	v_xor_b32_e32 v106, v105, v107
	v_lshlrev_b32_e32 v106, 4, v106
	v_lshl_add_u32 v164, v102, 6, v106
	v_or_b32_e32 v105, 2, v101
	v_xor_b32_e32 v106, v105, v107
	v_lshlrev_b32_e32 v106, 4, v106
	v_lshl_add_u32 v165, v102, 6, v106
	s_waitcnt lgkmcnt(0)
	s_barrier
	s_add_i32 m0, s44, 0
	s_nop 0
	global_load_lds_dwordx4 v[170:171], off
	global_load_lds_dwordx4 v[172:173], off offset:1024
	s_add_i32 m0, s45, 8192
	s_nop 0
	global_load_lds_dwordx4 v[174:175], off
	v_lshl_add_u64 v[170:171], v[170:171], 0, s[20:21]
	v_lshl_add_u64 v[172:173], v[172:173], 0, s[20:21]
	s_mov_b64 s[0:1], 0x1000
	v_lshl_add_u64 v[174:175], v[174:175], 0, s[0:1]
	ds_read_b128 v[112:115], v162 offset:13312
	ds_read_b128 v[116:119], v162 offset:17408
	ds_read_b128 v[120:123], v163 offset:13312
	ds_read_b128 v[124:127], v163 offset:17408
	ds_read_b128 v[96:99], v160 offset:13312
	ds_read_b128 v[100:103], v160 offset:17408
	ds_read_b128 v[104:107], v161 offset:13312
	ds_read_b128 v[108:111], v161 offset:17408
	v_max3_f32 v240, v48, v32, v49
	v_max3_f32 v241, v33, v50, v34
	v_max3_f32 v240, v51, v35, v240
	v_max3_f32 v241, v52, v36, v241
	v_max3_f32 v240, v53, v37, v240
	v_max3_f32 v241, v54, v38, v241
	v_max3_f32 v240, v55, v39, v240
	v_max3_f32 v241, v56, v40, v241
	v_max3_f32 v240, v57, v41, v240
	v_max3_f32 v241, v58, v42, v241
	v_max3_f32 v240, v59, v43, v240
	v_max3_f32 v241, v60, v44, v241
	v_max3_f32 v240, v61, v45, v240
	v_max3_f32 v241, v62, v46, v241
	v_max3_f32 v240, v63, v47, v240
	v_max_f32_e32 v240, v240, v241
	v_and_b32_e32 v181, 0x7fff, v180
	v_cmp_ne_u32_e32 vcc, 0, v181
	v_mov_b32_e32 v181, 0
	s_cbranch_vccnz .LBB0_268

; #define MFMA(a, b, c) __builtin_amdgcn_mfma_f32_32x32x16_bf16((a), (b), (c), 0, 0, 0)
; DI unsigned pack2(float a, float b) { f32x2v f = {a, b}; bf16x2v v = __builtin_convertvector(f, bf16x2v); return __builtin_bit_cast(unsigned, v); }
; DI float xhalf(float v) { return __shfl_xor(v, 32); }
;   template <int PAR>
;   DI void step(int t, f32x16 (&cur)[2], f32x16 (&nxt)[2]) {
;     if (t + 1 < nt) sstore_k(PAR ^ 1);
;     if (t > 0) sstore_v(PAR);
;     __syncthreads();
;     if (t + 1 < nt) qk(PAR ^ 1, nxt);
;     float mx = fmaxf(cur[0][0], cur[1][0]);
; #pragma unroll
;     for (int i = 1; i < 16; ++i) mx = fmaxf(fmaxf(cur[0][i], cur[1][i]), mx);
;     if (__builtin_amdgcn_ballot_w64(mx > ATT_THR) != 0ull) {
;       asm volatile("" ::: "memory");
;       mx = fmaxf(mx, xhalf(mx));
;       const float want = mref + fmaxf(mx, 0.f);
;       const float mn = __uint_as_float(pack2(want, 0.f) << 16);
;       const float d = mn - mref;
;       const float alpha = __builtin_amdgcn_exp2f(-d);
;       mref = mn;
;       l *= alpha;
; #pragma unroll
;       for (int a = 0; a < 2; ++a)
; #pragma unroll
;         for (int i = 0; i < 16; ++i) { o[a][i] *= alpha; cur[a][i] -= d; nxt[a][i] -= d; }
;       u32x4 q4 = {h == 0 ? (pack2(-mn, 0.f) & 0xffffu) : 0u, 0u, 0u, 0u};
;       qm = __builtin_bit_cast(bf16x8, q4);
;     }
;     float psum = 0.f;
; #pragma unroll
;     for (int kb2 = 0; kb2 < 2; ++kb2)
; #pragma unroll
;       for (int i = 0; i < 16; ++i) { const float pv = __builtin_amdgcn_exp2f(cur[kb2][i]); cur[kb2][i] = pv; psum += pv; }
;     l += psum;
;     if (t + 2 < nt) gload_k(t + 2);
;     if (t + 1 < nt) gload_v(t + 1);
;     const u16* vb = sV + PAR * VBUF + r * GP + h * 8;
; #pragma unroll
;     for (int kb2 = 0; kb2 < 2; ++kb2)
; #pragma unroll
;       for (int s2 = 0; s2 < 2; ++s2) {
;         u32x4 pk = {pack2(cur[kb2][8 * s2], cur[kb2][8 * s2 + 1]), pack2(cur[kb2][8 * s2 + 2], cur[kb2][8 * s2 + 3]),
;                     pack2(cur[kb2][8 * s2 + 4], cur[kb2][8 * s2 + 5]), pack2(cur[kb2][8 * s2 + 6], cur[kb2][8 * s2 + 7])};
;         const bf16x8 pf = __builtin_bit_cast(bf16x8, pk);
; #pragma unroll
;         for (int db = 0; db < 2; ++db) {
;           const bf16x8 a = *(const bf16x8*)(vb + db * 32 * GP + kb2 * 32 + s2 * 16);
;           o[db] = MFMA(a, pf, o[db]);
;         }
;       }
.Lmf_rareA_ret:
	v_exp_f32_e32 v48, v48
	v_exp_f32_e32 v49, v49
	v_exp_f32_e32 v50, v50
	v_add_f32_e32 v238, v48, v238
	v_exp_f32_e32 v51, v51
	v_add_f32_e32 v239, v49, v239
	v_exp_f32_e32 v52, v52
	v_add_f32_e32 v238, v50, v238
	s_waitcnt lgkmcnt(3)
	v_mfma_f32_32x32x16_bf16 v[80:95], v[96:99], v[136:139], 0
	ds_read_b128 v[96:99], v164 offset:21504
	v_exp_f32_e32 v53, v53
	v_add_f32_e32 v239, v51, v239
	v_exp_f32_e32 v54, v54
	v_add_f32_e32 v238, v52, v238
	v_exp_f32_e32 v55, v55
	s_waitcnt lgkmcnt(3)
	v_mfma_f32_32x32x16_bf16 v[64:79], v[100:103], v[136:139], 0
	ds_read_b128 v[100:103], v164 offset:23552
	v_add_f32_e32 v239, v53, v239
	v_cvt_pk_bf16_f32 v48, v48, v49
	v_add_f32_e32 v238, v54, v238
	v_cvt_pk_bf16_f32 v49, v50, v51
	v_add_f32_e32 v239, v55, v239
	s_waitcnt lgkmcnt(3)
	v_mfma_f32_32x32x16_bf16 v[80:95], v[104:107], v[140:143], v[80:95]
	ds_read_b128 v[104:107], v165 offset:21504
	v_cvt_pk_bf16_f32 v50, v52, v53
	v_cvt_pk_bf16_f32 v51, v54, v55
	v_exp_f32_e32 v56, v56
	v_exp_f32_e32 v57, v57
	v_exp_f32_e32 v58, v58
	s_waitcnt lgkmcnt(3)
	v_mfma_f32_32x32x16_bf16 v[64:79], v[108:111], v[140:143], v[64:79]
	ds_read_b128 v[108:111], v165 offset:23552
	v_add_f32_e32 v238, v56, v238
	v_exp_f32_e32 v59, v59
	v_add_f32_e32 v239, v57, v239
	v_exp_f32_e32 v60, v60
	v_add_f32_e32 v238, v58, v238
	s_waitcnt vmcnt(0)
	s_waitcnt lgkmcnt(0)
	s_barrier
	s_add_i32 s0, s31, -1
	s_cmp_ge_u32 s0, s19
	s_cselect_b64 s[14:15], -1, 0
	s_cmp_ge_u32 s31, s19
	s_cbranch_scc1 .Lmf_skipKA
	s_add_i32 m0, s44, 13312
	s_nop 0
	global_load_lds_dwordx4 v[170:171], off
	global_load_lds_dwordx4 v[172:173], off offset:1024
	s_add_i32 m0, s45, 21504
	s_nop 0
	global_load_lds_dwordx4 v[174:175], off
	v_lshl_add_u64 v[170:171], v[170:171], 0, s[20:21]
	v_lshl_add_u64 v[172:173], v[172:173], 0, s[20:21]
	s_mov_b64 s[0:1], 0x1000
	v_lshl_add_u64 v[174:175], v[174:175], 0, s[0:1]
.Lmf_skipKA:
	s_add_i32 m0, s44, 36864
	s_nop 0
	global_load_lds_dwordx4 v[176:177], off
	global_load_lds_dwordx4 v[178:179], off offset:1024
	v_mfma_f32_32x32x16_bf16 v[80:95], v[112:115], v[144:147], v[80:95]
	ds_read_b128 v[112:115], v166 offset:25600
	v_exp_f32_e32 v61, v61
	v_add_f32_e32 v239, v59, v239
	v_exp_f32_e32 v62, v62
	v_add_f32_e32 v238, v60, v238
	v_exp_f32_e32 v63, v63
	v_mfma_f32_32x32x16_bf16 v[64:79], v[116:119], v[144:147], v[64:79]
	ds_read_b128 v[116:119], v166 offset:29696
	v_add_f32_e32 v239, v61, v239
	v_cvt_pk_bf16_f32 v56, v56, v57
	v_add_f32_e32 v238, v62, v238
	v_cvt_pk_bf16_f32 v57, v58, v59
	v_add_f32_e32 v239, v63, v239
	v_mfma_f32_32x32x16_bf16 v[80:95], v[120:123], v[148:151], v[80:95]
	ds_read_b128 v[120:123], v167 offset:25600
	v_cvt_pk_bf16_f32 v58, v60, v61
	v_cvt_pk_bf16_f32 v59, v62, v63
	v_exp_f32_e32 v32, v32
	v_exp_f32_e32 v33, v33
	v_exp_f32_e32 v34, v34
	v_mfma_f32_32x32x16_bf16 v[64:79], v[124:127], v[148:151], v[64:79]
	ds_read_b128 v[124:127], v167 offset:29696
	v_add_f32_e32 v238, v32, v238
	v_exp_f32_e32 v35, v35
	v_add_f32_e32 v239, v33, v239
	v_exp_f32_e32 v36, v36
	v_add_f32_e32 v238, v34, v238
	v_mfma_f32_32x32x16_bf16 v[80:95], v[96:99], v[152:155], v[80:95]
	ds_read_b128 v[96:99], v168 offset:25600
	v_exp_f32_e32 v37, v37
	v_add_f32_e32 v239, v35, v239
	v_exp_f32_e32 v38, v38
	v_add_f32_e32 v238, v36, v238
	v_mfma_f32_32x32x16_bf16 v[64:79], v[100:103], v[152:155], v[64:79]
	ds_read_b128 v[100:103], v168 offset:29696
	v_exp_f32_e32 v39, v39
	v_add_f32_e32 v239, v37, v239
	v_cvt_pk_bf16_f32 v32, v32, v33
	v_add_f32_e32 v238, v38, v238
	v_mfma_f32_32x32x16_bf16 v[80:95], v[104:107], v[156:159], v[80:95]
	ds_read_b128 v[104:107], v169 offset:25600
	v_cvt_pk_bf16_f32 v33, v34, v35
	v_add_f32_e32 v239, v39, v239
	v_cvt_pk_bf16_f32 v34, v36, v37
	v_cvt_pk_bf16_f32 v35, v38, v39
	v_mfma_f32_32x32x16_bf16 v[64:79], v[108:111], v[156:159], v[64:79]
	ds_read_b128 v[108:111], v169 offset:29696
	v_exp_f32_e32 v40, v40
	v_exp_f32_e32 v41, v41
	v_exp_f32_e32 v42, v42
	v_add_f32_e32 v238, v40, v238
	s_waitcnt lgkmcnt(7)
	v_mfma_f32_32x32x16_bf16 v[16:31], v[112:115], v[48:51], v[16:31]
	ds_read_b128 v[112:115], v162
	v_exp_f32_e32 v43, v43
	v_add_f32_e32 v239, v41, v239
	v_exp_f32_e32 v44, v44
	v_add_f32_e32 v238, v42, v238
	s_waitcnt lgkmcnt(7)
	v_mfma_f32_32x32x16_bf16 v[0:15], v[116:119], v[48:51], v[0:15]
	ds_read_b128 v[116:119], v162 offset:4096
	v_exp_f32_e32 v45, v45
	v_add_f32_e32 v239, v43, v239
	v_exp_f32_e32 v46, v46
	v_add_f32_e32 v238, v44, v238
	s_waitcnt lgkmcnt(7)
	v_mfma_f32_32x32x16_bf16 v[16:31], v[120:123], v[56:59], v[16:31]
	ds_read_b128 v[120:123], v163
	v_exp_f32_e32 v47, v47
	v_add_f32_e32 v239, v45, v239
	v_cvt_pk_bf16_f32 v40, v40, v41
	v_add_f32_e32 v238, v46, v238
	s_waitcnt lgkmcnt(7)
	v_mfma_f32_32x32x16_bf16 v[0:15], v[124:127], v[56:59], v[0:15]
	ds_read_b128 v[124:127], v163 offset:4096
	v_cvt_pk_bf16_f32 v41, v42, v43
	v_add_f32_e32 v239, v47, v239
	v_cvt_pk_bf16_f32 v42, v44, v45
	v_cvt_pk_bf16_f32 v43, v46, v47
	s_waitcnt lgkmcnt(7)
	v_mfma_f32_32x32x16_bf16 v[16:31], v[96:99], v[32:35], v[16:31]
	ds_read_b128 v[96:99], v160
	v_max3_f32 v240, v80, v64, v81
	v_max3_f32 v241, v65, v82, v66
	v_max3_f32 v240, v83, v67, v240
	v_max3_f32 v241, v84, v68, v241
	s_waitcnt lgkmcnt(7)
	v_mfma_f32_32x32x16_bf16 v[0:15], v[100:103], v[32:35], v[0:15]
	ds_read_b128 v[100:103], v160 offset:4096
	v_max3_f32 v240, v85, v69, v240
	v_max3_f32 v241, v86, v70, v241
	v_max3_f32 v240, v87, v71, v240
	v_max3_f32 v241, v88, v72, v241
	s_waitcnt lgkmcnt(7)
	v_mfma_f32_32x32x16_bf16 v[16:31], v[104:107], v[40:43], v[16:31]
	ds_read_b128 v[104:107], v161
	v_max3_f32 v240, v89, v73, v240
	v_max3_f32 v241, v90, v74, v241
	v_max3_f32 v240, v91, v75, v240
	v_max3_f32 v241, v92, v76, v241
	s_waitcnt lgkmcnt(7)
	v_mfma_f32_32x32x16_bf16 v[0:15], v[108:111], v[40:43], v[0:15]
	ds_read_b128 v[108:111], v161 offset:4096
	v_max3_f32 v240, v93, v77, v240
	v_max3_f32 v241, v94, v78, v241
	v_max3_f32 v240, v95, v79, v240
	v_max_f32_e32 v240, v240, v241
	v_cmp_lt_f32_e32 vcc, s65, v240
	s_cbranch_vccnz .Lmf_rareB
; #define MFMA(a, b, c) __builtin_amdgcn_mfma_f32_32x32x16_bf16((a), (b), (c), 0, 0, 0)
; DI unsigned pack2(float a, float b) { f32x2v f = {a, b}; bf16x2v v = __builtin_convertvector(f, bf16x2v); return __builtin_bit_cast(unsigned, v); }
; DI float xhalf(float v) { return __shfl_xor(v, 32); }
;   template <int PAR>
;   DI void step(int t, f32x16 (&cur)[2], f32x16 (&nxt)[2]) {
;     if (t + 1 < nt) sstore_k(PAR ^ 1);
;     if (t > 0) sstore_v(PAR);
;     __syncthreads();
;     if (t + 1 < nt) qk(PAR ^ 1, nxt);
;     float mx = fmaxf(cur[0][0], cur[1][0]);
; #pragma unroll
;     for (int i = 1; i < 16; ++i) mx = fmaxf(fmaxf(cur[0][i], cur[1][i]), mx);
;     if (__builtin_amdgcn_ballot_w64(mx > ATT_THR) != 0ull) {
;       asm volatile("" ::: "memory");
;       mx = fmaxf(mx, xhalf(mx));
;       const float want = mref + fmaxf(mx, 0.f);
;       const float mn = __uint_as_float(pack2(want, 0.f) << 16);
;       const float d = mn - mref;
;       const float alpha = __builtin_amdgcn_exp2f(-d);
;       mref = mn;
;       l *= alpha;
; #pragma unroll
;       for (int a = 0; a < 2; ++a)
; #pragma unroll
;         for (int i = 0; i < 16; ++i) { o[a][i] *= alpha; cur[a][i] -= d; nxt[a][i] -= d; }
;       u32x4 q4 = {h == 0 ? (pack2(-mn, 0.f) & 0xffffu) : 0u, 0u, 0u, 0u};
;       qm = __builtin_bit_cast(bf16x8, q4);
;     }
;     float psum = 0.f;
; #pragma unroll
;     for (int kb2 = 0; kb2 < 2; ++kb2)
; #pragma unroll
;       for (int i = 0; i < 16; ++i) { const float pv = __builtin_amdgcn_exp2f(cur[kb2][i]); cur[kb2][i] = pv; psum += pv; }
;     l += psum;
;     if (t + 2 < nt) gload_k(t + 2);
;     if (t + 1 < nt) gload_v(t + 1);
;     const u16* vb = sV + PAR * VBUF + r * GP + h * 8;
; #pragma unroll
;     for (int kb2 = 0; kb2 < 2; ++kb2)
; #pragma unroll
;       for (int s2 = 0; s2 < 2; ++s2) {
;         u32x4 pk = {pack2(cur[kb2][8 * s2], cur[kb2][8 * s2 + 1]), pack2(cur[kb2][8 * s2 + 2], cur[kb2][8 * s2 + 3]),
;                     pack2(cur[kb2][8 * s2 + 4], cur[kb2][8 * s2 + 5]), pack2(cur[kb2][8 * s2 + 6], cur[kb2][8 * s2 + 7])};
;         const bf16x8 pf = __builtin_bit_cast(bf16x8, pk);
; #pragma unroll
;         for (int db = 0; db < 2; ++db) {
;           const bf16x8 a = *(const bf16x8*)(vb + db * 32 * GP + kb2 * 32 + s2 * 16);
;           o[db] = MFMA(a, pf, o[db]);
;         }
;       }
.Lmf_rareB_ret:
	v_exp_f32_e32 v80, v80
	v_exp_f32_e32 v81, v81
	v_exp_f32_e32 v82, v82
	v_add_f32_e32 v238, v80, v238
	v_exp_f32_e32 v83, v83
	v_add_f32_e32 v239, v81, v239
	v_exp_f32_e32 v84, v84
	v_add_f32_e32 v238, v82, v238
	s_waitcnt lgkmcnt(3)
	v_mfma_f32_32x32x16_bf16 v[48:63], v[96:99], v[136:139], 0
	ds_read_b128 v[96:99], v164 offset:8192
	v_exp_f32_e32 v85, v85
	v_add_f32_e32 v239, v83, v239
	v_exp_f32_e32 v86, v86
	v_add_f32_e32 v238, v84, v238
	v_exp_f32_e32 v87, v87
	s_waitcnt lgkmcnt(3)
	v_mfma_f32_32x32x16_bf16 v[32:47], v[100:103], v[136:139], 0
	ds_read_b128 v[100:103], v164 offset:10240
	v_add_f32_e32 v239, v85, v239
	v_cvt_pk_bf16_f32 v80, v80, v81
	v_add_f32_e32 v238, v86, v238
	v_cvt_pk_bf16_f32 v81, v82, v83
	v_add_f32_e32 v239, v87, v239
	s_waitcnt lgkmcnt(3)
	v_mfma_f32_32x32x16_bf16 v[48:63], v[104:107], v[140:143], v[48:63]
	ds_read_b128 v[104:107], v165 offset:8192
	v_cvt_pk_bf16_f32 v82, v84, v85
	v_cvt_pk_bf16_f32 v83, v86, v87
	v_exp_f32_e32 v88, v88
	v_exp_f32_e32 v89, v89
	v_exp_f32_e32 v90, v90
	s_waitcnt lgkmcnt(3)
	v_mfma_f32_32x32x16_bf16 v[32:47], v[108:111], v[140:143], v[32:47]
	ds_read_b128 v[108:111], v165 offset:10240
	v_add_f32_e32 v238, v88, v238
	v_exp_f32_e32 v91, v91
	v_add_f32_e32 v239, v89, v239
	v_exp_f32_e32 v92, v92
	v_add_f32_e32 v238, v90, v238
	s_waitcnt vmcnt(0)
	s_waitcnt lgkmcnt(0)
	s_barrier
	s_add_i32 s0, s31, 1
	s_cmp_ge_u32 s0, s19
	s_cbranch_scc1 .Lmf_skipKB
	s_add_i32 m0, s44, 0
	s_nop 0
	global_load_lds_dwordx4 v[170:171], off
	global_load_lds_dwordx4 v[172:173], off offset:1024
	s_add_i32 m0, s45, 8192
	s_nop 0
	global_load_lds_dwordx4 v[174:175], off
	v_lshl_add_u64 v[170:171], v[170:171], 0, s[20:21]
	v_lshl_add_u64 v[172:173], v[172:173], 0, s[20:21]
	s_mov_b64 s[0:1], 0x1000
	v_lshl_add_u64 v[174:175], v[174:175], 0, s[0:1]
.Lmf_skipKB:
	s_cmp_ge_u32 s31, s19
	s_cbranch_scc1 .Lmf_lastVB
	s_add_i32 m0, s44, 25472
	s_nop 0
	global_load_lds_dwordx4 v[176:177], off offset:128
	global_load_lds_dwordx4 v[178:179], off offset:1152
	v_lshl_add_u64 v[176:177], v[176:177], 0, s[84:85]
	v_lshl_add_u64 v[178:179], v[178:179], 0, s[84:85]
	s_branch .Lmf_skipVB

;   DI void qk(int buf, f32x16 (&s)[2]) {
;     const u16* kb = sK + buf * KBUF + sr * KP + h * 8;
; #pragma unroll
;     for (int kb2 = 0; kb2 < 2; ++kb2)
; #pragma unroll
;       for (int i = 0; i < 16; ++i) s[kb2][i] = 0.f;
; #pragma unroll
;     for (int ks = 0; ks < NKS; ++ks)
; #pragma unroll
;       for (int kb2 = 0; kb2 < 2; ++kb2) {
;   template <int PAR>
;   DI void step(int t, f32x16 (&cur)[2], f32x16 (&nxt)[2]) {
;     if (t + 1 < nt) sstore_k(PAR ^ 1);
;     if (t > 0) sstore_v(PAR);
;     __syncthreads();
;     if (t + 1 < nt) qk(PAR ^ 1, nxt);
;     float mx = fmaxf(cur[0][0], cur[1][0]);
; #pragma unroll
;     for (int i = 1; i < 16; ++i) mx = fmaxf(fmaxf(cur[0][i], cur[1][i]), mx);
;     if (__builtin_amdgcn_ballot_w64(mx > ATT_THR) != 0ull) {
;       asm volatile("" ::: "memory");
;       mx = fmaxf(mx, xhalf(mx));
;       const float want = mref + fmaxf(mx, 0.f);
;       const float mn = __uint_as_float(pack2(want, 0.f) << 16);
;       const float d = mn - mref;
;       const float alpha = __builtin_amdgcn_exp2f(-d);
;       mref = mn;
;       l *= alpha;
; #pragma unroll
;       for (int a = 0; a < 2; ++a)
; #pragma unroll
;         for (int i = 0; i < 16; ++i) { o[a][i] *= alpha; cur[a][i] -= d; nxt[a][i] -= d; }
;       u32x4 q4 = {h == 0 ? (pack2(-mn, 0.f) & 0xffffu) : 0u, 0u, 0u, 0u};
;       qm = __builtin_bit_cast(bf16x8, q4);
;     }
;     float psum = 0.f;
; #pragma unroll
;     for (int kb2 = 0; kb2 < 2; ++kb2)
; #pragma unroll
;       for (int i = 0; i < 16; ++i) { const float pv = __builtin_amdgcn_exp2f(cur[kb2][i]); cur[kb2][i] = pv; psum += pv; }
;     l += psum;
;     if (t + 2 < nt) gload_k(t + 2);
;     if (t + 1 < nt) gload_v(t + 1);
;     const u16* vb = sV + PAR * VBUF + r * GP + h * 8;
; #pragma unroll
;     for (int kb2 = 0; kb2 < 2; ++kb2)
; #pragma unroll
;       for (int s2 = 0; s2 < 2; ++s2) {
;         u32x4 pk = {pack2(cur[kb2][8 * s2], cur[kb2][8 * s2 + 1]), pack2(cur[kb2][8 * s2 + 2], cur[kb2][8 * s2 + 3]),
;                     pack2(cur[kb2][8 * s2 + 4], cur[kb2][8 * s2 + 5]), pack2(cur[kb2][8 * s2 + 6], cur[kb2][8 * s2 + 7])};
;         const bf16x8 pf = __builtin_bit_cast(bf16x8, pk);
; #pragma unroll
;         for (int db = 0; db < 2; ++db) {
;           const bf16x8 a = *(const bf16x8*)(vb + db * 32 * GP + kb2 * 32 + s2 * 16);
;           o[db] = MFMA(a, pf, o[db]);
;         }
;       }
.Lmf_skipVB:
	v_mfma_f32_32x32x16_bf16 v[48:63], v[112:115], v[144:147], v[48:63]
	ds_read_b128 v[112:115], v166 offset:36864
	v_exp_f32_e32 v93, v93
	v_add_f32_e32 v239, v91, v239
	v_exp_f32_e32 v94, v94
	v_add_f32_e32 v238, v92, v238
	v_exp_f32_e32 v95, v95
	v_mfma_f32_32x32x16_bf16 v[32:47], v[116:119], v[144:147], v[32:47]
	ds_read_b128 v[116:119], v166 offset:40960
	v_add_f32_e32 v239, v93, v239
	v_cvt_pk_bf16_f32 v88, v88, v89
	v_add_f32_e32 v238, v94, v238
	v_cvt_pk_bf16_f32 v89, v90, v91
	v_add_f32_e32 v239, v95, v239
	v_mfma_f32_32x32x16_bf16 v[48:63], v[120:123], v[148:151], v[48:63]
	ds_read_b128 v[120:123], v167 offset:36864
	v_cvt_pk_bf16_f32 v90, v92, v93
	v_cvt_pk_bf16_f32 v91, v94, v95
	v_exp_f32_e32 v64, v64
	v_exp_f32_e32 v65, v65
	v_exp_f32_e32 v66, v66
	v_mfma_f32_32x32x16_bf16 v[32:47], v[124:127], v[148:151], v[32:47]
	ds_read_b128 v[124:127], v167 offset:40960
	v_add_f32_e32 v238, v64, v238
	v_exp_f32_e32 v67, v67
	v_add_f32_e32 v239, v65, v239
	v_exp_f32_e32 v68, v68
	v_add_f32_e32 v238, v66, v238
	v_mfma_f32_32x32x16_bf16 v[48:63], v[96:99], v[152:155], v[48:63]
	ds_read_b128 v[96:99], v168 offset:36864
	v_exp_f32_e32 v69, v69
	v_add_f32_e32 v239, v67, v239
	v_exp_f32_e32 v70, v70
	v_add_f32_e32 v238, v68, v238
	v_mfma_f32_32x32x16_bf16 v[32:47], v[100:103], v[152:155], v[32:47]
	ds_read_b128 v[100:103], v168 offset:40960
	v_exp_f32_e32 v71, v71
	v_add_f32_e32 v239, v69, v239
	v_cvt_pk_bf16_f32 v64, v64, v65
	v_add_f32_e32 v238, v70, v238
	v_mfma_f32_32x32x16_bf16 v[48:63], v[104:107], v[156:159], v[48:63]
	ds_read_b128 v[104:107], v169 offset:36864
	v_cvt_pk_bf16_f32 v65, v66, v67
	v_add_f32_e32 v239, v71, v239
	v_cvt_pk_bf16_f32 v66, v68, v69
	v_cvt_pk_bf16_f32 v67, v70, v71
	v_mfma_f32_32x32x16_bf16 v[32:47], v[108:111], v[156:159], v[32:47]
	ds_read_b128 v[108:111], v169 offset:40960
	v_exp_f32_e32 v72, v72
	v_exp_f32_e32 v73, v73
	v_exp_f32_e32 v74, v74
	v_add_f32_e32 v238, v72, v238
	s_waitcnt lgkmcnt(7)
	v_mfma_f32_32x32x16_bf16 v[16:31], v[112:115], v[80:83], v[16:31]
	ds_read_b128 v[112:115], v162 offset:13312
	v_exp_f32_e32 v75, v75
	v_add_f32_e32 v239, v73, v239
	v_exp_f32_e32 v76, v76
	v_add_f32_e32 v238, v74, v238
	s_waitcnt lgkmcnt(7)
	v_mfma_f32_32x32x16_bf16 v[0:15], v[116:119], v[80:83], v[0:15]
	ds_read_b128 v[116:119], v162 offset:17408
	v_exp_f32_e32 v77, v77
	v_add_f32_e32 v239, v75, v239
	v_exp_f32_e32 v78, v78
	v_add_f32_e32 v238, v76, v238
	s_waitcnt lgkmcnt(7)
	v_mfma_f32_32x32x16_bf16 v[16:31], v[120:123], v[88:91], v[16:31]
	ds_read_b128 v[120:123], v163 offset:13312
	v_exp_f32_e32 v79, v79
	v_add_f32_e32 v239, v77, v239
	v_cvt_pk_bf16_f32 v72, v72, v73
	v_add_f32_e32 v238, v78, v238
	s_waitcnt lgkmcnt(7)
	v_mfma_f32_32x32x16_bf16 v[0:15], v[124:127], v[88:91], v[0:15]
	ds_read_b128 v[124:127], v163 offset:17408
	v_cvt_pk_bf16_f32 v73, v74, v75
	v_add_f32_e32 v239, v79, v239
	v_cvt_pk_bf16_f32 v74, v76, v77
	v_cvt_pk_bf16_f32 v75, v78, v79
	s_waitcnt lgkmcnt(7)
	v_mfma_f32_32x32x16_bf16 v[16:31], v[96:99], v[64:67], v[16:31]
	ds_read_b128 v[96:99], v160 offset:13312
	v_max3_f32 v240, v48, v32, v49
	v_max3_f32 v241, v33, v50, v34
	v_max3_f32 v240, v51, v35, v240
	v_max3_f32 v241, v52, v36, v241
	s_waitcnt lgkmcnt(7)
	v_mfma_f32_32x32x16_bf16 v[0:15], v[100:103], v[64:67], v[0:15]
	ds_read_b128 v[100:103], v160 offset:17408
	v_max3_f32 v240, v53, v37, v240
	v_max3_f32 v241, v54, v38, v241
	v_max3_f32 v240, v55, v39, v240
	v_max3_f32 v241, v56, v40, v241
	s_waitcnt lgkmcnt(7)
	v_mfma_f32_32x32x16_bf16 v[16:31], v[104:107], v[72:75], v[16:31]
	ds_read_b128 v[104:107], v161 offset:13312
	v_max3_f32 v240, v57, v41, v240
	v_max3_f32 v241, v58, v42, v241
	v_max3_f32 v240, v59, v43, v240
	v_max3_f32 v241, v60, v44, v241
	s_waitcnt lgkmcnt(7)
	v_mfma_f32_32x32x16_bf16 v[0:15], v[108:111], v[72:75], v[0:15]
	ds_read_b128 v[108:111], v161 offset:17408
	v_max3_f32 v240, v61, v45, v240
	v_max3_f32 v241, v62, v46, v241
	v_max3_f32 v240, v63, v47, v240
	v_max_f32_e32 v240, v240, v241
	v_lshl_add_u64 v[130:131], v[130:131], 0, s[84:85]
	v_lshl_add_u64 v[220:221], v[220:221], 0, s[84:85]
	s_mov_b32 s0, s31
	s_add_i32 s31, s31, 2
	s_cmp_lt_u32 s0, s19
	s_cbranch_scc1 .Lmf_top
	s_branch .Lm_fold

; #define MFMA(a, b, c) __builtin_amdgcn_mfma_f32_32x32x16_bf16((a), (b), (c), 0, 0, 0)
; DI unsigned pack2(float a, float b) { f32x2v f = {a, b}; bf16x2v v = __builtin_convertvector(f, bf16x2v); return __builtin_bit_cast(unsigned, v); }
; DI float xhalf(float v) { return __shfl_xor(v, 32); }
;   template <int PAR>
;   DI void step(int t, f32x16 (&cur)[2], f32x16 (&nxt)[2]) {
;     if (t + 1 < nt) sstore_k(PAR ^ 1);
;     if (t > 0) sstore_v(PAR);
;     __syncthreads();
;     if (t + 1 < nt) qk(PAR ^ 1, nxt);
;     float mx = fmaxf(cur[0][0], cur[1][0]);
; #pragma unroll
;     for (int i = 1; i < 16; ++i) mx = fmaxf(fmaxf(cur[0][i], cur[1][i]), mx);
;     if (__builtin_amdgcn_ballot_w64(mx > ATT_THR) != 0ull) {
;       asm volatile("" ::: "memory");
;       mx = fmaxf(mx, xhalf(mx));
;       const float want = mref + fmaxf(mx, 0.f);
;       const float mn = __uint_as_float(pack2(want, 0.f) << 16);
;       const float d = mn - mref;
;       const float alpha = __builtin_amdgcn_exp2f(-d);
;       mref = mn;
;       l *= alpha;
; #pragma unroll
;       for (int a = 0; a < 2; ++a)
; #pragma unroll
;         for (int i = 0; i < 16; ++i) { o[a][i] *= alpha; cur[a][i] -= d; nxt[a][i] -= d; }
;       u32x4 q4 = {h == 0 ? (pack2(-mn, 0.f) & 0xffffu) : 0u, 0u, 0u, 0u};
;       qm = __builtin_bit_cast(bf16x8, q4);
;     }
;     float psum = 0.f;
; #pragma unroll
;     for (int kb2 = 0; kb2 < 2; ++kb2)
; #pragma unroll
;       for (int i = 0; i < 16; ++i) { const float pv = __builtin_amdgcn_exp2f(cur[kb2][i]); cur[kb2][i] = pv; psum += pv; }
;     l += psum;
;     if (t + 2 < nt) gload_k(t + 2);
;     if (t + 1 < nt) gload_v(t + 1);
;     const u16* vb = sV + PAR * VBUF + r * GP + h * 8;
; #pragma unroll
;     for (int kb2 = 0; kb2 < 2; ++kb2)
; #pragma unroll
;       for (int s2 = 0; s2 < 2; ++s2) {
;         u32x4 pk = {pack2(cur[kb2][8 * s2], cur[kb2][8 * s2 + 1]), pack2(cur[kb2][8 * s2 + 2], cur[kb2][8 * s2 + 3]),
;                     pack2(cur[kb2][8 * s2 + 4], cur[kb2][8 * s2 + 5]), pack2(cur[kb2][8 * s2 + 6], cur[kb2][8 * s2 + 7])};
;         const bf16x8 pf = __builtin_bit_cast(bf16x8, pk);
; #pragma unroll
;         for (int db = 0; db < 2; ++db) {
;           const bf16x8 a = *(const bf16x8*)(vb + db * 32 * GP + kb2 * 32 + s2 * 16);
;           o[db] = MFMA(a, pf, o[db]);
;         }
;       }
.Lm_rareA_ret:
	v_exp_f32_e32 v48, v48
	v_exp_f32_e32 v49, v49
	v_exp_f32_e32 v50, v50
	v_add_f32_e32 v238, v48, v238
	v_exp_f32_e32 v51, v51
	v_add_f32_e32 v239, v49, v239
	v_exp_f32_e32 v52, v52
	v_add_f32_e32 v238, v50, v238
	s_waitcnt lgkmcnt(3)
	v_mfma_f32_32x32x16_bf16 v[80:95], v[96:99], v[136:139], 0
	ds_read_b128 v[96:99], v164 offset:21504
	v_exp_f32_e32 v53, v53
	v_add_f32_e32 v239, v51, v239
	v_exp_f32_e32 v54, v54
	v_add_f32_e32 v238, v52, v238
	s_waitcnt lgkmcnt(3)
	v_mfma_f32_32x32x16_bf16 v[64:79], v[100:103], v[136:139], 0
	ds_read_b128 v[100:103], v164 offset:23552
	v_exp_f32_e32 v55, v55
	v_add_f32_e32 v239, v53, v239
	v_cvt_pk_bf16_f32 v48, v48, v49
	v_add_f32_e32 v238, v54, v238
	s_waitcnt lgkmcnt(3)
	v_mfma_f32_32x32x16_bf16 v[80:95], v[104:107], v[140:143], v[80:95]
	ds_read_b128 v[104:107], v165 offset:21504
	v_cvt_pk_bf16_f32 v49, v50, v51
	v_add_f32_e32 v239, v55, v239
	v_cvt_pk_bf16_f32 v50, v52, v53
	v_cvt_pk_bf16_f32 v51, v54, v55
	s_waitcnt lgkmcnt(3)
	v_mfma_f32_32x32x16_bf16 v[64:79], v[108:111], v[140:143], v[64:79]
	ds_read_b128 v[108:111], v165 offset:23552
	v_exp_f32_e32 v56, v56
	v_exp_f32_e32 v57, v57
	v_exp_f32_e32 v58, v58
	v_add_f32_e32 v238, v56, v238
	s_waitcnt vmcnt(0)
	s_waitcnt lgkmcnt(0)
	s_barrier
	s_add_i32 s0, s31, -1
	s_cmp_ge_u32 s0, s19
	s_cselect_b64 s[14:15], -1, 0
	s_cmp_ge_u32 s31, s19
	s_cbranch_scc1 .Lm_skipKA
	s_add_i32 m0, s44, 13312
	s_nop 0
	global_load_lds_dwordx4 v[170:171], off
	global_load_lds_dwordx4 v[172:173], off offset:1024
	s_add_i32 m0, s45, 21504
	s_nop 0
	global_load_lds_dwordx4 v[174:175], off
	v_lshl_add_u64 v[170:171], v[170:171], 0, s[20:21]
	v_lshl_add_u64 v[172:173], v[172:173], 0, s[20:21]
	s_mov_b64 s[0:1], 0x1000
	v_lshl_add_u64 v[174:175], v[174:175], 0, s[0:1]
; #define MFMA(a, b, c) __builtin_amdgcn_mfma_f32_32x32x16_bf16((a), (b), (c), 0, 0, 0)
; DI unsigned pack2(float a, float b) { f32x2v f = {a, b}; bf16x2v v = __builtin_convertvector(f, bf16x2v); return __builtin_bit_cast(unsigned, v); }
; DI float xhalf(float v) { return __shfl_xor(v, 32); }
;   template <int PAR>
;   DI void step(int t, f32x16 (&cur)[2], f32x16 (&nxt)[2]) {
;     if (t + 1 < nt) sstore_k(PAR ^ 1);
;     if (t > 0) sstore_v(PAR);
;     __syncthreads();
;     if (t + 1 < nt) qk(PAR ^ 1, nxt);
;     float mx = fmaxf(cur[0][0], cur[1][0]);
; #pragma unroll
;     for (int i = 1; i < 16; ++i) mx = fmaxf(fmaxf(cur[0][i], cur[1][i]), mx);
;     if (__builtin_amdgcn_ballot_w64(mx > ATT_THR) != 0ull) {
;       asm volatile("" ::: "memory");
;       mx = fmaxf(mx, xhalf(mx));
;       const float want = mref + fmaxf(mx, 0.f);
;       const float mn = __uint_as_float(pack2(want, 0.f) << 16);
;       const float d = mn - mref;
;       const float alpha = __builtin_amdgcn_exp2f(-d);
;       mref = mn;
;       l *= alpha;
; #pragma unroll
;       for (int a = 0; a < 2; ++a)
; #pragma unroll
;         for (int i = 0; i < 16; ++i) { o[a][i] *= alpha; cur[a][i] -= d; nxt[a][i] -= d; }
;       u32x4 q4 = {h == 0 ? (pack2(-mn, 0.f) & 0xffffu) : 0u, 0u, 0u, 0u};
;       qm = __builtin_bit_cast(bf16x8, q4);
;     }
;     float psum = 0.f;
; #pragma unroll
;     for (int kb2 = 0; kb2 < 2; ++kb2)
; #pragma unroll
;       for (int i = 0; i < 16; ++i) { const float pv = __builtin_amdgcn_exp2f(cur[kb2][i]); cur[kb2][i] = pv; psum += pv; }
;     l += psum;
;     if (t + 2 < nt) gload_k(t + 2);
;     if (t + 1 < nt) gload_v(t + 1);
;     const u16* vb = sV + PAR * VBUF + r * GP + h * 8;
; #pragma unroll
;     for (int kb2 = 0; kb2 < 2; ++kb2)
; #pragma unroll
;       for (int s2 = 0; s2 < 2; ++s2) {
;         u32x4 pk = {pack2(cur[kb2][8 * s2], cur[kb2][8 * s2 + 1]), pack2(cur[kb2][8 * s2 + 2], cur[kb2][8 * s2 + 3]),
;                     pack2(cur[kb2][8 * s2 + 4], cur[kb2][8 * s2 + 5]), pack2(cur[kb2][8 * s2 + 6], cur[kb2][8 * s2 + 7])};
;         const bf16x8 pf = __builtin_bit_cast(bf16x8, pk);
; #pragma unroll
;         for (int db = 0; db < 2; ++db) {
;           const bf16x8 a = *(const bf16x8*)(vb + db * 32 * GP + kb2 * 32 + s2 * 16);
;           o[db] = MFMA(a, pf, o[db]);
;         }
;       }
.Lm_skipKA:
	s_add_i32 m0, s44, 36864
	s_nop 0
	global_load_lds_dwordx4 v[176:177], off
	global_load_lds_dwordx4 v[178:179], off offset:1024
	v_mfma_f32_32x32x16_bf16 v[80:95], v[112:115], v[144:147], v[80:95]
	ds_read_b128 v[112:115], v166 offset:25600
	v_exp_f32_e32 v59, v59
	v_add_f32_e32 v239, v57, v239
	v_exp_f32_e32 v60, v60
	v_add_f32_e32 v238, v58, v238
	v_mfma_f32_32x32x16_bf16 v[64:79], v[116:119], v[144:147], v[64:79]
	ds_read_b128 v[116:119], v166 offset:29696
	v_exp_f32_e32 v61, v61
	v_add_f32_e32 v239, v59, v239
	v_exp_f32_e32 v62, v62
	v_add_f32_e32 v238, v60, v238
	v_mfma_f32_32x32x16_bf16 v[80:95], v[120:123], v[148:151], v[80:95]
	ds_read_b128 v[120:123], v167 offset:25600
	v_exp_f32_e32 v63, v63
	v_add_f32_e32 v239, v61, v239
	v_cvt_pk_bf16_f32 v56, v56, v57
	v_add_f32_e32 v238, v62, v238
	v_mfma_f32_32x32x16_bf16 v[64:79], v[124:127], v[148:151], v[64:79]
	ds_read_b128 v[124:127], v167 offset:29696
	v_cvt_pk_bf16_f32 v57, v58, v59
	v_add_f32_e32 v239, v63, v239
	v_cvt_pk_bf16_f32 v58, v60, v61
	v_cvt_pk_bf16_f32 v59, v62, v63
	v_mfma_f32_32x32x16_bf16 v[80:95], v[96:99], v[152:155], v[80:95]
	ds_read_b128 v[96:99], v168 offset:25600
	v_exp_f32_e32 v32, v32
	v_exp_f32_e32 v33, v33
	v_exp_f32_e32 v34, v34
	v_add_f32_e32 v238, v32, v238
	v_mfma_f32_32x32x16_bf16 v[64:79], v[100:103], v[152:155], v[64:79]
	ds_read_b128 v[100:103], v168 offset:29696
	v_exp_f32_e32 v35, v35
	v_add_f32_e32 v239, v33, v239
	v_exp_f32_e32 v36, v36
	v_add_f32_e32 v238, v34, v238
	v_mfma_f32_32x32x16_bf16 v[80:95], v[104:107], v[156:159], v[80:95]
	ds_read_b128 v[104:107], v169 offset:25600
	v_exp_f32_e32 v37, v37
	v_add_f32_e32 v239, v35, v239
	v_exp_f32_e32 v38, v38
	v_add_f32_e32 v238, v36, v238
	v_mfma_f32_32x32x16_bf16 v[64:79], v[108:111], v[156:159], v[64:79]
	ds_read_b128 v[108:111], v169 offset:29696
	v_exp_f32_e32 v39, v39
	v_add_f32_e32 v239, v37, v239
	v_cvt_pk_bf16_f32 v32, v32, v33
	v_add_f32_e32 v238, v38, v238
	v_mfma_f32_32x32x16_bf16 v[80:95], v[132:135], v[180:183], v[80:95]
	v_cvt_pk_bf16_f32 v33, v34, v35
	v_add_f32_e32 v239, v39, v239
	v_cvt_pk_bf16_f32 v34, v36, v37
	v_cvt_pk_bf16_f32 v35, v38, v39
	v_mfma_f32_32x32x16_bf16 v[64:79], v[132:135], v[180:183], v[64:79]
	v_exp_f32_e32 v40, v40
	v_exp_f32_e32 v41, v41
	v_exp_f32_e32 v42, v42
	v_add_f32_e32 v238, v40, v238
	s_waitcnt lgkmcnt(7)
	v_mfma_f32_32x32x16_bf16 v[16:31], v[112:115], v[48:51], v[16:31]
	ds_read_b128 v[112:115], v162
	v_exp_f32_e32 v43, v43
	v_add_f32_e32 v239, v41, v239
	v_exp_f32_e32 v44, v44
	v_add_f32_e32 v238, v42, v238
	s_waitcnt lgkmcnt(7)
	v_mfma_f32_32x32x16_bf16 v[0:15], v[116:119], v[48:51], v[0:15]
	ds_read_b128 v[116:119], v162 offset:4096
	v_exp_f32_e32 v45, v45
	v_add_f32_e32 v239, v43, v239
	v_exp_f32_e32 v46, v46
	v_add_f32_e32 v238, v44, v238
	s_waitcnt lgkmcnt(7)
	v_mfma_f32_32x32x16_bf16 v[16:31], v[120:123], v[56:59], v[16:31]
	ds_read_b128 v[120:123], v163
	v_exp_f32_e32 v47, v47
	v_add_f32_e32 v239, v45, v239
	v_cvt_pk_bf16_f32 v40, v40, v41
	v_add_f32_e32 v238, v46, v238
	s_waitcnt lgkmcnt(7)
	v_mfma_f32_32x32x16_bf16 v[0:15], v[124:127], v[56:59], v[0:15]
	ds_read_b128 v[124:127], v163 offset:4096
	v_cvt_pk_bf16_f32 v41, v42, v43
	v_add_f32_e32 v239, v47, v239
	v_cvt_pk_bf16_f32 v42, v44, v45
	v_cvt_pk_bf16_f32 v43, v46, v47
	s_waitcnt lgkmcnt(7)
	v_mfma_f32_32x32x16_bf16 v[16:31], v[96:99], v[32:35], v[16:31]
	ds_read_b128 v[96:99], v160
	v_max3_f32 v240, v80, v64, v81
	v_max3_f32 v241, v65, v82, v66
	v_max3_f32 v240, v83, v67, v240
	v_max3_f32 v241, v84, v68, v241
	s_waitcnt lgkmcnt(7)
	v_mfma_f32_32x32x16_bf16 v[0:15], v[100:103], v[32:35], v[0:15]
	ds_read_b128 v[100:103], v160 offset:4096
	v_max3_f32 v240, v85, v69, v240
	v_max3_f32 v241, v86, v70, v241
	v_max3_f32 v240, v87, v71, v240
	v_max3_f32 v241, v88, v72, v241
	s_waitcnt lgkmcnt(7)
	v_mfma_f32_32x32x16_bf16 v[16:31], v[104:107], v[40:43], v[16:31]
	ds_read_b128 v[104:107], v161
	v_max3_f32 v240, v89, v73, v240
	v_max3_f32 v241, v90, v74, v241
	v_max3_f32 v240, v91, v75, v240
	v_max3_f32 v241, v92, v76, v241
	s_waitcnt lgkmcnt(7)
	v_mfma_f32_32x32x16_bf16 v[0:15], v[108:111], v[40:43], v[0:15]
	ds_read_b128 v[108:111], v161 offset:4096
	v_max3_f32 v240, v93, v77, v240
	v_max3_f32 v241, v94, v78, v241
	v_max3_f32 v240, v95, v79, v240
	v_max_f32_e32 v240, v240, v241
	v_cmp_lt_f32_e32 vcc, s65, v240
	s_cbranch_vccnz .Lm_rareB
.Lm_rareB_ret:
	v_exp_f32_e32 v80, v80
	v_exp_f32_e32 v81, v81
	v_exp_f32_e32 v82, v82
	v_add_f32_e32 v238, v80, v238
	v_exp_f32_e32 v83, v83
	v_add_f32_e32 v239, v81, v239
	v_exp_f32_e32 v84, v84
	v_add_f32_e32 v238, v82, v238
	s_waitcnt lgkmcnt(3)
	v_mfma_f32_32x32x16_bf16 v[48:63], v[96:99], v[136:139], 0
	ds_read_b128 v[96:99], v164 offset:8192
	v_exp_f32_e32 v85, v85
	v_add_f32_e32 v239, v83, v239
	v_exp_f32_e32 v86, v86
	v_add_f32_e32 v238, v84, v238
	s_waitcnt lgkmcnt(3)
	v_mfma_f32_32x32x16_bf16 v[32:47], v[100:103], v[136:139], 0
	ds_read_b128 v[100:103], v164 offset:10240
	v_exp_f32_e32 v87, v87
	v_add_f32_e32 v239, v85, v239
	v_cvt_pk_bf16_f32 v80, v80, v81
	v_add_f32_e32 v238, v86, v238
	s_waitcnt lgkmcnt(3)
	v_mfma_f32_32x32x16_bf16 v[48:63], v[104:107], v[140:143], v[48:63]
	ds_read_b128 v[104:107], v165 offset:8192
	v_cvt_pk_bf16_f32 v81, v82, v83
	v_add_f32_e32 v239, v87, v239
	v_cvt_pk_bf16_f32 v82, v84, v85
	v_cvt_pk_bf16_f32 v83, v86, v87
	s_waitcnt lgkmcnt(3)
	v_mfma_f32_32x32x16_bf16 v[32:47], v[108:111], v[140:143], v[32:47]
	ds_read_b128 v[108:111], v165 offset:10240
	v_exp_f32_e32 v88, v88
	v_exp_f32_e32 v89, v89
	v_exp_f32_e32 v90, v90
	v_add_f32_e32 v238, v88, v238
	s_waitcnt vmcnt(0)
	s_waitcnt lgkmcnt(0)
	s_barrier
	s_add_i32 s0, s31, 1
	s_cmp_ge_u32 s0, s19
	s_cbranch_scc1 .Lm_skipKB
	s_add_i32 m0, s44, 0
	s_nop 0
	global_load_lds_dwordx4 v[170:171], off
	global_load_lds_dwordx4 v[172:173], off offset:1024
	s_add_i32 m0, s45, 8192
	s_nop 0
	global_load_lds_dwordx4 v[174:175], off
	v_lshl_add_u64 v[170:171], v[170:171], 0, s[20:21]
	v_lshl_add_u64 v[172:173], v[172:173], 0, s[20:21]
	s_mov_b64 s[0:1], 0x1000
	v_lshl_add_u64 v[174:175], v[174:175], 0, s[0:1]

;   DI void qk(int buf, f32x16 (&s)[2]) {
;     const u16* kb = sK + buf * KBUF + sr * KP + h * 8;
; #pragma unroll
;     for (int kb2 = 0; kb2 < 2; ++kb2)
; #pragma unroll
;       for (int i = 0; i < 16; ++i) s[kb2][i] = 0.f;
; #pragma unroll
;     for (int ks = 0; ks < NKS; ++ks)
; #pragma unroll
;       for (int kb2 = 0; kb2 < 2; ++kb2) {
;   template <int PAR>
;   DI void step(int t, f32x16 (&cur)[2], f32x16 (&nxt)[2]) {
;     if (t + 1 < nt) sstore_k(PAR ^ 1);
;     if (t > 0) sstore_v(PAR);
;     __syncthreads();
;     if (t + 1 < nt) qk(PAR ^ 1, nxt);
;     float mx = fmaxf(cur[0][0], cur[1][0]);
; #pragma unroll
;     for (int i = 1; i < 16; ++i) mx = fmaxf(fmaxf(cur[0][i], cur[1][i]), mx);
;     if (__builtin_amdgcn_ballot_w64(mx > ATT_THR) != 0ull) {
;       asm volatile("" ::: "memory");
;       mx = fmaxf(mx, xhalf(mx));
;       const float want = mref + fmaxf(mx, 0.f);
;       const float mn = __uint_as_float(pack2(want, 0.f) << 16);
;       const float d = mn - mref;
;       const float alpha = __builtin_amdgcn_exp2f(-d);
;       mref = mn;
;       l *= alpha;
; #pragma unroll
;       for (int a = 0; a < 2; ++a)
; #pragma unroll
;         for (int i = 0; i < 16; ++i) { o[a][i] *= alpha; cur[a][i] -= d; nxt[a][i] -= d; }
;       u32x4 q4 = {h == 0 ? (pack2(-mn, 0.f) & 0xffffu) : 0u, 0u, 0u, 0u};
;       qm = __builtin_bit_cast(bf16x8, q4);
;     }
;     float psum = 0.f;
; #pragma unroll
;     for (int kb2 = 0; kb2 < 2; ++kb2)
; #pragma unroll
;       for (int i = 0; i < 16; ++i) { const float pv = __builtin_amdgcn_exp2f(cur[kb2][i]); cur[kb2][i] = pv; psum += pv; }
;     l += psum;
;     if (t + 2 < nt) gload_k(t + 2);
;     if (t + 1 < nt) gload_v(t + 1);
;     const u16* vb = sV + PAR * VBUF + r * GP + h * 8;
; #pragma unroll
;     for (int kb2 = 0; kb2 < 2; ++kb2)
; #pragma unroll
;       for (int s2 = 0; s2 < 2; ++s2) {
;         u32x4 pk = {pack2(cur[kb2][8 * s2], cur[kb2][8 * s2 + 1]), pack2(cur[kb2][8 * s2 + 2], cur[kb2][8 * s2 + 3]),
;                     pack2(cur[kb2][8 * s2 + 4], cur[kb2][8 * s2 + 5]), pack2(cur[kb2][8 * s2 + 6], cur[kb2][8 * s2 + 7])};
;         const bf16x8 pf = __builtin_bit_cast(bf16x8, pk);
; #pragma unroll
;         for (int db = 0; db < 2; ++db) {
;           const bf16x8 a = *(const bf16x8*)(vb + db * 32 * GP + kb2 * 32 + s2 * 16);
;           o[db] = MFMA(a, pf, o[db]);
;         }
;       }
.Lm_skipVB:
	v_mfma_f32_32x32x16_bf16 v[48:63], v[112:115], v[144:147], v[48:63]
	ds_read_b128 v[112:115], v166 offset:36864
	v_exp_f32_e32 v91, v91
	v_add_f32_e32 v239, v89, v239
	v_exp_f32_e32 v92, v92
	v_add_f32_e32 v238, v90, v238
	v_mfma_f32_32x32x16_bf16 v[32:47], v[116:119], v[144:147], v[32:47]
	ds_read_b128 v[116:119], v166 offset:40960
	v_exp_f32_e32 v93, v93
	v_add_f32_e32 v239, v91, v239
	v_exp_f32_e32 v94, v94
	v_add_f32_e32 v238, v92, v238
	v_mfma_f32_32x32x16_bf16 v[48:63], v[120:123], v[148:151], v[48:63]
	ds_read_b128 v[120:123], v167 offset:36864
	v_exp_f32_e32 v95, v95
	v_add_f32_e32 v239, v93, v239
	v_cvt_pk_bf16_f32 v88, v88, v89
	v_add_f32_e32 v238, v94, v238
	v_mfma_f32_32x32x16_bf16 v[32:47], v[124:127], v[148:151], v[32:47]
	ds_read_b128 v[124:127], v167 offset:40960
	v_cvt_pk_bf16_f32 v89, v90, v91
	v_add_f32_e32 v239, v95, v239
	v_cvt_pk_bf16_f32 v90, v92, v93
	v_cvt_pk_bf16_f32 v91, v94, v95
	v_mfma_f32_32x32x16_bf16 v[48:63], v[96:99], v[152:155], v[48:63]
	ds_read_b128 v[96:99], v168 offset:36864
	v_exp_f32_e32 v64, v64
	v_exp_f32_e32 v65, v65
	v_exp_f32_e32 v66, v66
	v_add_f32_e32 v238, v64, v238
	v_mfma_f32_32x32x16_bf16 v[32:47], v[100:103], v[152:155], v[32:47]
	ds_read_b128 v[100:103], v168 offset:40960
	v_exp_f32_e32 v67, v67
	v_add_f32_e32 v239, v65, v239
	v_exp_f32_e32 v68, v68
	v_add_f32_e32 v238, v66, v238
	v_mfma_f32_32x32x16_bf16 v[48:63], v[104:107], v[156:159], v[48:63]
	ds_read_b128 v[104:107], v169 offset:36864
	v_exp_f32_e32 v69, v69
	v_add_f32_e32 v239, v67, v239
	v_exp_f32_e32 v70, v70
	v_add_f32_e32 v238, v68, v238
	v_mfma_f32_32x32x16_bf16 v[32:47], v[108:111], v[156:159], v[32:47]
	ds_read_b128 v[108:111], v169 offset:40960
	v_exp_f32_e32 v71, v71
	v_add_f32_e32 v239, v69, v239
	v_cvt_pk_bf16_f32 v64, v64, v65
	v_add_f32_e32 v238, v70, v238
	v_mfma_f32_32x32x16_bf16 v[48:63], v[132:135], v[180:183], v[48:63]
	v_cvt_pk_bf16_f32 v65, v66, v67
	v_add_f32_e32 v239, v71, v239
	v_cvt_pk_bf16_f32 v66, v68, v69
	v_cvt_pk_bf16_f32 v67, v70, v71
	v_mfma_f32_32x32x16_bf16 v[32:47], v[132:135], v[180:183], v[32:47]
	v_exp_f32_e32 v72, v72
	v_exp_f32_e32 v73, v73
	v_exp_f32_e32 v74, v74
	v_add_f32_e32 v238, v72, v238
	s_waitcnt lgkmcnt(7)
	v_mfma_f32_32x32x16_bf16 v[16:31], v[112:115], v[80:83], v[16:31]
	ds_read_b128 v[112:115], v162 offset:13312
	v_exp_f32_e32 v75, v75
	v_add_f32_e32 v239, v73, v239
	v_exp_f32_e32 v76, v76
	v_add_f32_e32 v238, v74, v238
	s_waitcnt lgkmcnt(7)
	v_mfma_f32_32x32x16_bf16 v[0:15], v[116:119], v[80:83], v[0:15]
	ds_read_b128 v[116:119], v162 offset:17408
	v_exp_f32_e32 v77, v77
	v_add_f32_e32 v239, v75, v239
	v_exp_f32_e32 v78, v78
	v_add_f32_e32 v238, v76, v238
	s_waitcnt lgkmcnt(7)
	v_mfma_f32_32x32x16_bf16 v[16:31], v[120:123], v[88:91], v[16:31]
	ds_read_b128 v[120:123], v163 offset:13312
	v_exp_f32_e32 v79, v79
	v_add_f32_e32 v239, v77, v239
	v_cvt_pk_bf16_f32 v72, v72, v73
	v_add_f32_e32 v238, v78, v238
	s_waitcnt lgkmcnt(7)
	v_mfma_f32_32x32x16_bf16 v[0:15], v[124:127], v[88:91], v[0:15]
	ds_read_b128 v[124:127], v163 offset:17408
	v_cvt_pk_bf16_f32 v73, v74, v75
	v_add_f32_e32 v239, v79, v239
	v_cvt_pk_bf16_f32 v74, v76, v77
	v_cvt_pk_bf16_f32 v75, v78, v79
	s_waitcnt lgkmcnt(7)
	v_mfma_f32_32x32x16_bf16 v[16:31], v[96:99], v[64:67], v[16:31]
	ds_read_b128 v[96:99], v160 offset:13312
	v_max3_f32 v240, v48, v32, v49
	v_max3_f32 v241, v33, v50, v34
	v_max3_f32 v240, v51, v35, v240
	v_max3_f32 v241, v52, v36, v241
	s_waitcnt lgkmcnt(7)
	v_mfma_f32_32x32x16_bf16 v[0:15], v[100:103], v[64:67], v[0:15]
	ds_read_b128 v[100:103], v160 offset:17408
	v_max3_f32 v240, v53, v37, v240
	v_max3_f32 v241, v54, v38, v241
	v_max3_f32 v240, v55, v39, v240
	v_max3_f32 v241, v56, v40, v241
	s_waitcnt lgkmcnt(7)
	v_mfma_f32_32x32x16_bf16 v[16:31], v[104:107], v[72:75], v[16:31]
	ds_read_b128 v[104:107], v161 offset:13312
	v_max3_f32 v240, v57, v41, v240
	v_max3_f32 v241, v58, v42, v241
	v_max3_f32 v240, v59, v43, v240
	v_max3_f32 v241, v60, v44, v241
	s_waitcnt lgkmcnt(7)
	v_mfma_f32_32x32x16_bf16 v[0:15], v[108:111], v[72:75], v[0:15]
	ds_read_b128 v[108:111], v161 offset:17408
	v_max3_f32 v240, v61, v45, v240
	v_max3_f32 v241, v62, v46, v241
	v_max3_f32 v240, v63, v47, v240
	v_max_f32_e32 v240, v240, v241
	v_lshl_add_u64 v[130:131], v[130:131], 0, s[84:85]
	v_lshl_add_u64 v[220:221], v[220:221], 0, s[84:85]
	s_mov_b32 s0, s31
	s_add_i32 s31, s31, 2
	s_cmp_lt_u32 s0, s19
	s_cbranch_scc1 .LBB0_268
	s_branch .Lm_fold
